# MLA: issue bubbles every 3 VALU slots in the older half's softmax segment
# speedup vs baseline: 1.0216x; 1.0216x over previous
.Lmla_nowrite_A:
	s_waitcnt lgkmcnt(9)
	v_mfma_f32_32x32x16_bf16 v[64:79], v[178:181], v[100:103], v[64:79]
	s_waitcnt lgkmcnt(8)
	v_mfma_f32_32x32x16_bf16 v[48:63], v[198:201], v[100:103], v[48:63]
	s_setprio 0
	s_nop 10
	v_max_f32_e32 v172, v64, v65
	v_max3_f32 v173, v66, v67, v49
	v_max3_f32 v172, v172, v48, v50
	s_nop 1
	v_max3_f32 v172, v172, v51, v68
	v_max3_f32 v173, v173, v70, v71
	v_max3_f32 v172, v172, v69, v52
	s_nop 1
	v_max3_f32 v173, v173, v54, v55
	v_max3_f32 v172, v172, v53, v72
	v_max3_f32 v173, v173, v74, v75
	s_nop 1
	v_max3_f32 v172, v172, v73, v56
	v_max3_f32 v173, v173, v58, v59
	v_max3_f32 v172, v172, v57, v76
	s_nop 1
	v_max3_f32 v173, v173, v78, v79
	v_max3_f32 v172, v172, v77, v60
	v_max3_f32 v173, v173, v62, v63
	s_nop 1
	v_max3_f32 v172, v172, v61, v173
	v_mov_b32_e32 v173, v172
	s_nop 1
	v_permlane32_swap_b32_e32 v172, v173
	s_nop 1
	v_max_f32_e32 v177, v172, v173
	v_cmp_lt_f32_e32 vcc, s14, v177
	s_cbranch_vccz .Lmla_norescale_A
	v_max_f32_e32 v172, s15, v177
	v_max_f32_e32 v173, 0xc2c80000, v172
	v_exp_f32_e64 v173, -v173
	s_nop 1
	v_add_f32_e32 v156, v156, v172
	v_sub_f32_e32 v48, v48, v172
	v_sub_f32_e32 v49, v49, v172
	s_nop 1
	v_sub_f32_e32 v50, v50, v172
	v_sub_f32_e32 v51, v51, v172
	v_sub_f32_e32 v52, v52, v172
	s_nop 1
	v_sub_f32_e32 v53, v53, v172
	v_sub_f32_e32 v54, v54, v172
	v_sub_f32_e32 v55, v55, v172
	s_nop 1
	v_sub_f32_e32 v56, v56, v172
	v_sub_f32_e32 v57, v57, v172
	v_sub_f32_e32 v58, v58, v172
	s_nop 1
	v_sub_f32_e32 v59, v59, v172
	v_sub_f32_e32 v60, v60, v172
	v_sub_f32_e32 v61, v61, v172
	s_nop 1
	v_sub_f32_e32 v62, v62, v172
	v_sub_f32_e32 v63, v63, v172
	v_sub_f32_e32 v64, v64, v172
	s_nop 1
	v_sub_f32_e32 v65, v65, v172
	v_sub_f32_e32 v66, v66, v172
	v_sub_f32_e32 v67, v67, v172
	s_nop 1
	v_sub_f32_e32 v68, v68, v172
	v_sub_f32_e32 v69, v69, v172
	v_sub_f32_e32 v70, v70, v172
	s_nop 1
	v_sub_f32_e32 v71, v71, v172
	v_sub_f32_e32 v72, v72, v172
	v_sub_f32_e32 v73, v73, v172
	s_nop 1
	v_sub_f32_e32 v74, v74, v172
	v_sub_f32_e32 v75, v75, v172
	v_sub_f32_e32 v76, v76, v172
	s_nop 1
	v_sub_f32_e32 v77, v77, v172
	v_sub_f32_e32 v78, v78, v172
	v_sub_f32_e32 v79, v79, v172
	s_nop 1
	v_mul_f32_e32 v0, v0, v173
	v_mul_f32_e32 v1, v1, v173
	v_mul_f32_e32 v2, v2, v173
	s_nop 1
	v_mul_f32_e32 v3, v3, v173
	v_mul_f32_e32 v4, v4, v173
	v_mul_f32_e32 v5, v5, v173
	s_nop 1
	v_mul_f32_e32 v6, v6, v173
	v_mul_f32_e32 v7, v7, v173
	v_mul_f32_e32 v8, v8, v173
	s_nop 1
	v_mul_f32_e32 v9, v9, v173
	v_mul_f32_e32 v10, v10, v173
	v_mul_f32_e32 v11, v11, v173
	s_nop 1
	v_mul_f32_e32 v12, v12, v173
	v_mul_f32_e32 v13, v13, v173
	v_mul_f32_e32 v14, v14, v173
	s_nop 1
	v_mul_f32_e32 v15, v15, v173
	v_mul_f32_e32 v16, v16, v173
	v_mul_f32_e32 v17, v17, v173
	s_nop 1
	v_mul_f32_e32 v18, v18, v173
	v_mul_f32_e32 v19, v19, v173
	v_mul_f32_e32 v20, v20, v173
	s_nop 1
	v_mul_f32_e32 v21, v21, v173
	v_mul_f32_e32 v22, v22, v173
	v_mul_f32_e32 v23, v23, v173
	s_nop 1
	v_mul_f32_e32 v24, v24, v173
	v_mul_f32_e32 v25, v25, v173
	v_mul_f32_e32 v26, v26, v173
	s_nop 1
	v_mul_f32_e32 v27, v27, v173
	v_mul_f32_e32 v28, v28, v173
	v_mul_f32_e32 v29, v29, v173
	s_nop 1
	v_mul_f32_e32 v30, v30, v173
	v_mul_f32_e32 v31, v31, v173
	v_mul_f32_e32 v157, v157, v173
	s_nop 1
	v_sub_f32_e32 v32, 0, v156
	v_mov_b32_e32 v33, v32
	v_mov_b32_e32 v34, v32
	s_nop 1
	v_mov_b32_e32 v35, v32
	v_mov_b32_e32 v36, v32
	v_mov_b32_e32 v37, v32
	s_nop 1
	v_mov_b32_e32 v38, v32
	v_mov_b32_e32 v39, v32
	v_mov_b32_e32 v40, v32
	s_nop 1
	v_mov_b32_e32 v41, v32
	v_mov_b32_e32 v42, v32
	v_mov_b32_e32 v43, v32
	s_nop 1
	v_mov_b32_e32 v44, v32
	v_mov_b32_e32 v45, v32
	v_mov_b32_e32 v46, v32
	s_nop 1
	v_mov_b32_e32 v47, v32
.Lmla_norescale_A:
	v_exp_f32_e32 v64, v64
	v_exp_f32_e32 v65, v65
	s_nop 1
	v_exp_f32_e32 v66, v66
	v_exp_f32_e32 v67, v67
	s_nop 1
	v_exp_f32_e32 v68, v68
	v_exp_f32_e32 v69, v69
	s_nop 1
	v_exp_f32_e32 v70, v70
	v_exp_f32_e32 v71, v71
	s_nop 1
	v_cvt_pk_bf16_f32 v234, v64, v65
	v_cvt_pk_bf16_f32 v235, v66, v67
	v_cvt_pk_bf16_f32 v236, v68, v69
	s_nop 1
	v_cvt_pk_bf16_f32 v237, v70, v71
	v_exp_f32_e32 v72, v72
	s_nop 1
	v_exp_f32_e32 v73, v73
	v_exp_f32_e32 v74, v74
	s_nop 1
	v_exp_f32_e32 v75, v75
	v_exp_f32_e32 v76, v76
	s_nop 1
	v_exp_f32_e32 v77, v77
	v_exp_f32_e32 v78, v78
	s_nop 1
	v_exp_f32_e32 v79, v79
	v_cvt_pk_bf16_f32 v238, v72, v73
	s_nop 1
	v_cvt_pk_bf16_f32 v239, v74, v75
	v_cvt_pk_bf16_f32 v240, v76, v77
	v_cvt_pk_bf16_f32 v241, v78, v79
	s_nop 1
	v_exp_f32_e32 v48, v48
	v_exp_f32_e32 v49, v49
	s_nop 1
	v_exp_f32_e32 v50, v50
	v_exp_f32_e32 v51, v51
	s_nop 1
	v_exp_f32_e32 v52, v52
	v_exp_f32_e32 v53, v53
	s_nop 1
	v_exp_f32_e32 v54, v54
	v_exp_f32_e32 v55, v55
	s_nop 1
	v_cvt_pk_bf16_f32 v242, v48, v49
	v_cvt_pk_bf16_f32 v243, v50, v51
	v_cvt_pk_bf16_f32 v244, v52, v53
	s_nop 1
	v_cvt_pk_bf16_f32 v245, v54, v55
	v_exp_f32_e32 v56, v56
	s_nop 1
	v_exp_f32_e32 v57, v57
	v_exp_f32_e32 v58, v58
	s_nop 1
	v_exp_f32_e32 v59, v59
	v_exp_f32_e32 v60, v60
	s_nop 1
	v_exp_f32_e32 v61, v61
	v_exp_f32_e32 v62, v62
	s_nop 1
	v_exp_f32_e32 v63, v63
	v_cvt_pk_bf16_f32 v246, v56, v57
	s_nop 1
	v_cvt_pk_bf16_f32 v247, v58, v59
	v_cvt_pk_bf16_f32 v248, v60, v61
	v_cvt_pk_bf16_f32 v249, v62, v63
	s_nop 1
	v_add_f32_e32 v172, v64, v65
	v_add_f32_e32 v173, v66, v67
	v_add_f32_e32 v177, v68, v69
	s_nop 1
	v_add_f32_e32 v64, v70, v71
	v_add_f32_e32 v172, v172, v72
	v_add_f32_e32 v173, v173, v73
	s_nop 1
	v_add_f32_e32 v177, v177, v74
	v_add_f32_e32 v64, v64, v75
	v_add_f32_e32 v172, v172, v76
	s_nop 1
	v_add_f32_e32 v173, v173, v77
	v_add_f32_e32 v177, v177, v78
	v_add_f32_e32 v64, v64, v79
	s_nop 1
	v_add_f32_e32 v172, v172, v48
	v_add_f32_e32 v173, v173, v49
	v_add_f32_e32 v177, v177, v50
	s_nop 1
	v_add_f32_e32 v64, v64, v51
	v_add_f32_e32 v172, v172, v52
	v_add_f32_e32 v173, v173, v53
	s_nop 1
	v_add_f32_e32 v177, v177, v54
	v_add_f32_e32 v64, v64, v55
	v_add_f32_e32 v172, v172, v56
	s_nop 1
	v_add_f32_e32 v173, v173, v57
	v_add_f32_e32 v177, v177, v58
	v_add_f32_e32 v64, v64, v59
	s_nop 1
	v_add_f32_e32 v172, v172, v60
	v_add_f32_e32 v173, v173, v61
	v_add_f32_e32 v177, v177, v62
	s_nop 1
	v_add_f32_e32 v64, v64, v63
	v_add_f32_e32 v172, v172, v173
	v_add_f32_e32 v177, v177, v64
	s_nop 1
	v_add_f32_e32 v172, v172, v177
	v_add_f32_e32 v157, v157, v172
	s_mov_b32 s14, 0x41000000
	s_mov_b32 s15, 0
	s_waitcnt lgkmcnt(0)
	s_barrier
	s_add_i32 s28, s28, 1
	s_cmp_lt_i32 s28, s22
	s_cbranch_scc1 .Lmla_A_loop
	v_mfma_f32_32x32x16_bf16 v[16:31], v[202:205], v[234:237], v[16:31]
	v_mfma_f32_32x32x16_bf16 v[0:15], v[218:221], v[234:237], v[0:15]
	v_mfma_f32_32x32x16_bf16 v[16:31], v[206:209], v[238:241], v[16:31]
	v_mfma_f32_32x32x16_bf16 v[0:15], v[222:225], v[238:241], v[0:15]
	v_mfma_f32_32x32x16_bf16 v[16:31], v[210:213], v[242:245], v[16:31]
	v_mfma_f32_32x32x16_bf16 v[0:15], v[226:229], v[242:245], v[0:15]
	v_mfma_f32_32x32x16_bf16 v[16:31], v[214:217], v[246:249], v[16:31]
	v_mfma_f32_32x32x16_bf16 v[0:15], v[230:233], v[246:249], v[0:15]
	s_branch .Lmla_exit
